# layer-0 mixer pooling: the 15 previous-rows loads of each prompt unit batched (one wait) instead of 15 serialized load/wait round trips
# speedup vs baseline: 1.0044x; 1.0017x over previous
; __device__ __forceinline__ void sgu_prompt_unit(const Params& p, LAS unsigned char* lds, int unit, int tid, int wave, int lane) {
;     ...
; #pragma unroll
;         for (int k = 0; k < 16; ++k) prev[k] = (ch > 0) ? bf1(pp[(r0 - 16 + k) * 1536]) : 0.f;
.LBB0_227:
	s_cmp_lg_u32 s11, 0
	s_cselect_b64 s[2:3], -1, 0
	s_and_b64 vcc, exec, s[2:3]
	v_cndmask_b32_e64 v1, 0, 1, s[2:3]
	v_mov_b32_e32 v42, 0
	v_cmp_ne_u32_e64 s[0:1], 1, v1
	s_andn2_b64 vcc, exec, s[2:3]
	s_mul_i32 s7, s91, 0xc00
	s_cbranch_vccnz .LBB0_229
	v_mad_u64_u32 v[2:3], s[4:5], s90, v188, v[98:99]
	v_add_u32_e32 v1, s7, v3
	v_add_co_u32_e32 v2, vcc, 0xffff5000, v2
	s_nop 1
	v_addc_co_u32_e32 v3, vcc, -1, v1, vcc
	global_load_ushort v42, v[2:3], off offset:-1024
.LBB0_229:
	v_mov_b32_e32 v34, 0
	s_and_b64 vcc, exec, s[0:1]
	v_mov_b32_e32 v52, 0
	s_cbranch_vccnz .LBB0_231
	v_mad_u64_u32 v[2:3], s[4:5], s90, v188, v[98:99]
	v_add_u32_e32 v1, s7, v3
	v_add_co_u32_e32 v2, vcc, 0xffff6000, v2
	s_nop 1
	v_addc_co_u32_e32 v3, vcc, -1, v1, vcc
	global_load_ushort v52, v[2:3], off offset:-2048
.LBB0_231:
	s_and_b64 vcc, exec, s[0:1]
	s_cbranch_vccnz .LBB0_233
	v_mad_u64_u32 v[2:3], s[4:5], s90, v188, v[98:99]
	v_add_u32_e32 v1, s7, v3
	v_add_co_u32_e32 v2, vcc, 0xffff7000, v2
	s_nop 1
	v_addc_co_u32_e32 v3, vcc, -1, v1, vcc
	global_load_ushort v34, v[2:3], off offset:-3072
.LBB0_233:
	v_mov_b32_e32 v36, 0
	s_and_b64 vcc, exec, s[0:1]
	v_mov_b32_e32 v50, 0
	s_cbranch_vccnz .LBB0_235
	v_mad_u64_u32 v[2:3], s[4:5], s90, v188, v[98:99]
	v_add_u32_e32 v1, s7, v3
	v_add_co_u32_e32 v2, vcc, 0xffff7000, v2
	s_nop 1
	v_addc_co_u32_e32 v3, vcc, -1, v1, vcc
	global_load_ushort v50, v[2:3], off
.LBB0_235:
	s_and_b64 vcc, exec, s[0:1]
	s_cbranch_vccnz .LBB0_237
	v_mad_u64_u32 v[2:3], s[4:5], s90, v188, v[98:99]
	v_add_u32_e32 v1, s7, v3
	v_add_co_u32_e32 v2, vcc, 0xffff8000, v2
	s_nop 1
	v_addc_co_u32_e32 v3, vcc, -1, v1, vcc
	global_load_ushort v36, v[2:3], off offset:-1024
.LBB0_237:
	v_mov_b32_e32 v38, 0
	s_and_b64 vcc, exec, s[0:1]
	v_mov_b32_e32 v54, 0
	s_cbranch_vccnz .LBB0_239
	v_mad_u64_u32 v[2:3], s[4:5], s90, v188, v[98:99]
	v_add_u32_e32 v1, s7, v3
	v_add_co_u32_e32 v2, vcc, 0xffff9000, v2
	s_nop 1
	v_addc_co_u32_e32 v3, vcc, -1, v1, vcc
	global_load_ushort v54, v[2:3], off offset:-2048
.LBB0_239:
	s_and_b64 vcc, exec, s[0:1]
	s_cbranch_vccnz .LBB0_241
	v_mad_u64_u32 v[2:3], s[4:5], s90, v188, v[98:99]
	v_add_u32_e32 v1, s7, v3
	v_add_co_u32_e32 v2, vcc, 0xffffa000, v2
	s_nop 1
	v_addc_co_u32_e32 v3, vcc, -1, v1, vcc
	global_load_ushort v38, v[2:3], off offset:-3072
.LBB0_241:
	v_mov_b32_e32 v40, 0
	s_and_b64 vcc, exec, s[0:1]
	v_mov_b32_e32 v56, 0
	s_cbranch_vccnz .LBB0_243
	v_mad_u64_u32 v[2:3], s[4:5], s90, v188, v[98:99]
	v_add_u32_e32 v1, s7, v3
	v_add_co_u32_e32 v2, vcc, 0xffffa000, v2
	s_nop 1
	v_addc_co_u32_e32 v3, vcc, -1, v1, vcc
	global_load_ushort v56, v[2:3], off
.LBB0_243:
	s_and_b64 vcc, exec, s[0:1]
	s_cbranch_vccnz .LBB0_245
	v_mad_u64_u32 v[2:3], s[4:5], s90, v188, v[98:99]
	v_add_u32_e32 v1, s7, v3
	v_add_co_u32_e32 v2, vcc, 0xffffb000, v2
	s_nop 1
	v_addc_co_u32_e32 v3, vcc, -1, v1, vcc
	global_load_ushort v40, v[2:3], off offset:-1024
.LBB0_245:
	v_mov_b32_e32 v44, 0
	s_and_b64 vcc, exec, s[0:1]
	v_mov_b32_e32 v58, 0
	s_cbranch_vccnz .LBB0_247
	v_mad_u64_u32 v[2:3], s[4:5], s90, v188, v[98:99]
	v_add_u32_e32 v1, s7, v3
	v_add_co_u32_e32 v2, vcc, 0xffffc000, v2
	s_nop 1
	v_addc_co_u32_e32 v3, vcc, -1, v1, vcc
	global_load_ushort v58, v[2:3], off offset:-2048
.LBB0_247:
	s_and_b64 vcc, exec, s[0:1]
	s_cbranch_vccnz .LBB0_249
	v_mad_u64_u32 v[2:3], s[4:5], s90, v188, v[98:99]
	v_add_u32_e32 v1, s7, v3
	v_add_co_u32_e32 v2, vcc, 0xffffd000, v2
	s_nop 1
	v_addc_co_u32_e32 v3, vcc, -1, v1, vcc
	global_load_ushort v44, v[2:3], off offset:-3072
.LBB0_249:
	s_and_b64 vcc, exec, s[0:1]
	s_cbranch_vccnz .LBB0_278
	v_mad_u64_u32 v[2:3], s[4:5], s90, v188, v[98:99]
	v_add_u32_e32 v1, s7, v3
	v_add_co_u32_e32 v2, vcc, 0xffffd000, v2
	s_nop 1
	v_addc_co_u32_e32 v3, vcc, -1, v1, vcc
	global_load_ushort v60, v[2:3], off
	s_and_b64 vcc, exec, s[2:3]
	s_mul_hi_u32 s14, s90, 0xc00
	s_mul_i32 s2, s90, 0xc00
	s_cbranch_vccz .LBB0_279
.LBB0_251:
	v_mad_u64_u32 v[2:3], s[4:5], s90, v188, v[98:99]
	v_add_u32_e32 v1, s7, v3
	v_add_co_u32_e32 v2, vcc, 0xffffe000, v2
	s_add_i32 s3, s14, s7
	s_nop 0
	v_addc_co_u32_e32 v3, vcc, -1, v1, vcc
	global_load_ushort v48, v[2:3], off offset:-1024
	s_cbranch_execnz .LBB0_253

; __device__ __forceinline__ unsigned f2bf(float f) { return pg8::cvt_pk_bf16(f, 0.f) & 0xffffu; }
; __device__ __forceinline__ void sgu_prompt_unit(const Params& p, LAS unsigned char* lds, int unit, int tid, int wave, int lane) {
;     ...
;         for (int k = 0; k < 16; ++k) prev[k] = (ch > 0) ? bf1(pp[(r0 - 16 + k) * 1536]) : 0.f;
;         bf16 nxt[16];
; #pragma unroll
;         for (int k = 0; k < 16; ++k) nxt[k] = pp[(r0 + k) * 1536];
; #pragma unroll 1
;         for (int blk = 0; blk < 8; ++blk) {
; #pragma unroll
;             for (int k = 0; k < 16; ++k) cur[k] = bf1(nxt[k]);
;             if (blk < 7) {
; #pragma unroll
;                 for (int k = 0; k < 16; ++k) nxt[k] = pp[(r0 + 16 * (blk + 1) + k) * 1536]; }
;             pool_dispatch(gi, prev, cur, o, ch * 128 + 16 * blk, ch == 0 && blk == 0);
; #pragma unroll
;             for (int k = 0; k < 16; ++k) AO[(r0 + 16 * blk + k) * 1024 + 512 + c] = (bf16)f2bf(o[k]);
.LBB0_253:
	v_mov_b32_e32 v47, 0
	s_and_b64 vcc, exec, s[0:1]
	v_lshl_add_u64 v[2:3], v[98:99], 0, s[2:3]
	v_mov_b32_e32 v46, 0
	s_cbranch_vccnz .LBB0_255
	v_add_co_u32_e32 v4, vcc, 0xfffff000, v2
	s_nop 1
	v_addc_co_u32_e32 v5, vcc, -1, v3, vcc
	global_load_ushort v46, v[4:5], off offset:-2048
.LBB0_255:
	s_and_b64 vcc, exec, s[0:1]
	s_cbranch_vccnz .LBB0_257
	global_load_ushort v47, v[2:3], off offset:-3072
.LBB0_257:
	v_add_co_u32_e32 v4, vcc, 0x1000, v2
	global_load_ushort v32, v[2:3], off
	global_load_ushort v33, v[2:3], off offset:3072
	v_addc_co_u32_e32 v5, vcc, 0, v3, vcc
	global_load_ushort v37, v[4:5], off offset:2048
	v_add_co_u32_e32 v4, vcc, 0x2000, v2
	s_mov_b32 s0, 0x8000
	s_nop 0
	v_addc_co_u32_e32 v5, vcc, 0, v3, vcc
	global_load_ushort v39, v[4:5], off offset:1024
	v_add_co_u32_e32 v4, vcc, 0x3000, v2
	s_cmp_eq_u32 s11, 63
	s_nop 0
	v_addc_co_u32_e32 v5, vcc, 0, v3, vcc
	global_load_ushort v41, v[4:5], off
	global_load_ushort v43, v[4:5], off offset:3072
	v_add_co_u32_e32 v4, vcc, 0x4000, v2
	s_mul_i32 s4, s86, 0x7800
	s_nop 0
	v_addc_co_u32_e32 v5, vcc, 0, v3, vcc
	global_load_ushort v35, v[4:5], off offset:2048
	v_add_co_u32_e32 v4, vcc, 0x5000, v2
	s_mul_hi_i32 s3, s86, 0x7800
	s_nop 0
	v_addc_co_u32_e32 v5, vcc, 0, v3, vcc
	global_load_ushort v1, v[4:5], off offset:1024
	v_add_co_u32_e32 v4, vcc, 0x6000, v2
	s_mul_i32 s2, s6, 0x60000
	s_nop 0
	v_addc_co_u32_e32 v5, vcc, 0, v3, vcc
	global_load_ushort v57, v[4:5], off
	global_load_ushort v49, v[4:5], off offset:3072
	v_add_co_u32_e32 v4, vcc, 0x7000, v2
	s_mov_b32 s16, 0
	s_nop 0
	v_addc_co_u32_e32 v5, vcc, 0, v3, vcc
	global_load_ushort v59, v[4:5], off offset:2048
	v_add_co_u32_e32 v4, vcc, s0, v2
	s_cselect_b64 s[0:1], -1, 0
	s_nop 0
	v_addc_co_u32_e32 v5, vcc, 0, v3, vcc
	global_load_ushort v61, v[4:5], off offset:1024
	v_add_co_u32_e32 v4, vcc, 0x9000, v2
	s_add_u32 s4, s92, s4
	s_nop 0
	v_addc_co_u32_e32 v5, vcc, 0, v3, vcc
	global_load_ushort v62, v[4:5], off
	global_load_ushort v63, v[4:5], off offset:3072
	v_add_co_u32_e32 v4, vcc, 0xa000, v2
	s_addc_u32 s5, s93, s3
	s_nop 0
	v_addc_co_u32_e32 v5, vcc, 0, v3, vcc
	v_add_co_u32_e32 v2, vcc, 0xb000, v2
	global_load_ushort v64, v[4:5], off offset:2048
	s_nop 0
	v_addc_co_u32_e32 v3, vcc, 0, v3, vcc
	global_load_ushort v65, v[2:3], off offset:1024
	v_lshl_add_u64 v[30:31], v[74:75], 2, s[4:5]
	s_mov_b64 s[4:5], 0x8400000
	v_lshl_add_u64 v[2:3], v[30:31], 0, s[4:5]
	s_mov_b64 s[4:5], 0x8400800
	v_lshl_add_u64 v[4:5], v[30:31], 0, s[4:5]
	s_mov_b64 s[4:5], 0x8401000
	v_lshl_add_u64 v[6:7], v[30:31], 0, s[4:5]
	s_mov_b64 s[4:5], 0x8401800
	v_lshl_add_u64 v[8:9], v[30:31], 0, s[4:5]
	s_mov_b64 s[4:5], 0x8402000
	v_lshl_add_u64 v[10:11], v[30:31], 0, s[4:5]
	s_mov_b64 s[4:5], 0x8402800
	v_lshl_add_u64 v[12:13], v[30:31], 0, s[4:5]
	s_mov_b64 s[4:5], 0x8403000
	v_lshl_add_u64 v[14:15], v[30:31], 0, s[4:5]
	s_mov_b64 s[4:5], 0x8403800
	v_lshl_add_u64 v[16:17], v[30:31], 0, s[4:5]
	s_mov_b64 s[4:5], 0x8404000
	v_lshl_add_u64 v[18:19], v[30:31], 0, s[4:5]
	s_mov_b64 s[4:5], 0x8404800
	v_lshl_add_u64 v[20:21], v[30:31], 0, s[4:5]
	s_mov_b64 s[4:5], 0x8405000
	v_lshl_add_u64 v[22:23], v[30:31], 0, s[4:5]
	s_mov_b64 s[4:5], 0x8405800
	v_lshl_add_u64 v[24:25], v[30:31], 0, s[4:5]
	s_mov_b64 s[4:5], 0x8406000
	v_lshl_add_u64 v[26:27], v[30:31], 0, s[4:5]
	s_mov_b64 s[4:5], 0x8406800
	v_lshl_add_u64 v[28:29], v[30:31], 0, s[4:5]
	s_mov_b64 s[4:5], 0x8407000
	v_lshl_add_u64 v[30:31], v[30:31], 0, s[4:5]
	s_mul_i32 s4, s86, 0x1800000
	s_mul_hi_i32 s3, s86, 0x1800000
	s_add_u32 s2, s4, s2
	s_addc_u32 s3, s3, 0
	s_waitcnt vmcnt(10)
	v_lshlrev_b32_e32 v42, 16, v42
	v_lshlrev_b32_e32 v52, 16, v52
	v_lshlrev_b32_e32 v34, 16, v34
	v_lshlrev_b32_e32 v50, 16, v50
	v_lshlrev_b32_e32 v36, 16, v36
	v_lshlrev_b32_e32 v54, 16, v54
	v_lshlrev_b32_e32 v38, 16, v38
	v_lshlrev_b32_e32 v56, 16, v56
	v_lshlrev_b32_e32 v40, 16, v40
	v_lshlrev_b32_e32 v58, 16, v58
	v_lshlrev_b32_e32 v44, 16, v44
	v_lshlrev_b32_e32 v60, 16, v60
	v_lshlrev_b32_e32 v48, 16, v48
	v_lshlrev_b32_e32 v46, 16, v46
	v_lshlrev_b32_e32 v47, 16, v47
	s_nop 0
	s_nop 0
	s_nop 0
	s_nop 0
	s_nop 0
	s_nop 0
	s_nop 0
	s_nop 0
	s_nop 0
	s_nop 0
	s_nop 0
	s_nop 0
	s_nop 0
	s_nop 0
	s_nop 0
	v_perm_b32 v45, v39, v43, s8
	v_perm_b32 v51, v37, v41, s8
	v_perm_b32 v53, v33, v39, s8
	s_waitcnt vmcnt(9)
	v_perm_b32 v35, v41, v35, s8
	v_perm_b32 v55, v32, v37, s8
	v_lshl_add_u64 v[32:33], v[90:91], 0, s[2:3]
	s_mov_b64 s[4:5], 0
	s_mov_b32 s15, 0
	s_waitcnt vmcnt(5)
	v_perm_b32 v57, v57, v59, s8
	s_waitcnt vmcnt(4)
	v_perm_b32 v49, v49, v61, s8
	s_waitcnt vmcnt(3)
	v_perm_b32 v43, v59, v62, s8
	s_waitcnt vmcnt(2)
	v_perm_b32 v41, v61, v63, s8
	s_waitcnt vmcnt(1)
	v_perm_b32 v39, v62, v64, s8
	s_waitcnt vmcnt(0)
	v_perm_b32 v37, v63, v65, s8
	s_branch .LBB0_259
